# grid barrier: non-leader workgroups poll the cross-XCC TOPGEN word directly (skip the per-XCC XGEN relay hop), on top of v021
# speedup vs baseline: 1.0030x; 1.0021x over previous
.LBB0_283:
	s_or_b64 exec, exec, s[4:5]
	v_cvt_f32_u32_e32 v4, v2
	s_waitcnt vmcnt(0)
	v_readfirstlane_b32 s3, v3
	v_sub_u32_e32 v3, 0, v2
	v_rcp_iflag_f32_e32 v4, v4
	v_add_u32_e32 v5, s3, v1
	v_mul_f32_e32 v4, 0x4f7ffffe, v4
	v_cvt_u32_f32_e32 v4, v4
	v_mul_lo_u32 v1, v3, v4
	v_mul_hi_u32 v1, v4, v1
	v_add_u32_e32 v1, v4, v1
	v_mul_hi_u32 v1, v5, v1
	v_mul_lo_u32 v3, v1, v2
	v_sub_u32_e32 v3, v5, v3
	v_add_u32_e32 v4, 1, v1
	v_cmp_ge_u32_e32 vcc, v3, v2
	s_nop 1
	v_cndmask_b32_e32 v1, v1, v4, vcc
	v_sub_u32_e32 v4, v3, v2
	v_cndmask_b32_e32 v3, v3, v4, vcc
	v_add_u32_e32 v4, 1, v1
	v_cmp_ge_u32_e32 vcc, v3, v2
	v_add_u32_e32 v3, 1, v5
	s_nop 0
	v_cndmask_b32_e32 v1, v1, v4, vcc
	v_mul_lo_u32 v4, v2, v1
	v_add_u32_e32 v2, v4, v2
	v_cmp_ne_u32_e32 vcc, v3, v2
	s_and_saveexec_b64 s[4:5], vcc
	s_xor_b64 s[4:5], exec, s[4:5]
	s_cbranch_execz .LBB0_297
	v_readlane_b32 s6, v251, 43
	v_readlane_b32 s7, v251, 44
	s_waitcnt lgkmcnt(0)
	s_nop 3
	global_load_dword v0, v97, s[6:7] sc1
	s_waitcnt vmcnt(0)
	v_cmp_eq_u32_e32 vcc, v0, v1
	s_and_saveexec_b64 s[16:17], vcc
	s_cbranch_execz .LBB0_296
	s_mov_b32 s3, 1
	s_mov_b64 s[24:25], 0
	s_branch .LBB0_287

.LBB0_291:
	v_readlane_b32 s6, v251, 43
	v_readlane_b32 s7, v251, 44
	s_add_i32 s3, s3, 1
	s_mov_b64 s[40:41], -1
	s_nop 2
	global_load_dword v0, v97, s[6:7] sc1
	s_waitcnt vmcnt(0)
	v_cmp_ne_u32_e32 vcc, v0, v1
	s_orn2_b64 s[38:39], vcc, exec
	s_branch .LBB0_286

.LBB0_1143:
	v_readlane_b32 s6, v251, 43
	v_readlane_b32 s7, v251, 44
	s_add_i32 s3, s3, 1
	s_mov_b64 s[42:43], -1
	s_nop 2
	global_load_dword v0, v97, s[6:7] sc1
	s_waitcnt vmcnt(0)
	v_cmp_ne_u32_e32 vcc, v0, v1
	s_orn2_b64 s[40:41], vcc, exec
	s_branch .LBB0_1138

.LBB0_1338:
	s_or_b64 exec, exec, s[4:5]
	v_cvt_f32_u32_e32 v4, v2
	s_waitcnt vmcnt(0)
	v_readfirstlane_b32 s2, v3
	v_sub_u32_e32 v3, 0, v2
	v_rcp_iflag_f32_e32 v4, v4
	v_add_u32_e32 v5, s2, v1
	v_mul_f32_e32 v4, 0x4f7ffffe, v4
	v_cvt_u32_f32_e32 v4, v4
	v_mul_lo_u32 v1, v3, v4
	v_mul_hi_u32 v1, v4, v1
	v_add_u32_e32 v1, v4, v1
	v_mul_hi_u32 v1, v5, v1
	v_mul_lo_u32 v3, v1, v2
	v_sub_u32_e32 v3, v5, v3
	v_add_u32_e32 v4, 1, v1
	v_cmp_ge_u32_e32 vcc, v3, v2
	s_nop 1
	v_cndmask_b32_e32 v1, v1, v4, vcc
	v_sub_u32_e32 v4, v3, v2
	v_cndmask_b32_e32 v3, v3, v4, vcc
	v_add_u32_e32 v4, 1, v1
	v_cmp_ge_u32_e32 vcc, v3, v2
	v_add_u32_e32 v3, 1, v5
	s_nop 0
	v_cndmask_b32_e32 v1, v1, v4, vcc
	v_mul_lo_u32 v4, v2, v1
	v_add_u32_e32 v2, v4, v2
	v_cmp_ne_u32_e32 vcc, v3, v2
	s_and_saveexec_b64 s[2:3], vcc
	s_xor_b64 s[4:5], exec, s[2:3]
	s_cbranch_execz .LBB0_1369
	v_readlane_b32 s2, v251, 43
	v_readlane_b32 s3, v251, 44
	s_waitcnt lgkmcnt(0)
	s_nop 3
	global_load_dword v0, v97, s[2:3] sc1
	s_waitcnt vmcnt(0)
	v_cmp_eq_u32_e32 vcc, v0, v1
	s_and_saveexec_b64 s[16:17], vcc
	s_cbranch_execz .LBB0_1368
	s_mov_b32 s2, 1
	s_mov_b64 s[24:25], 0
	s_branch .LBB0_1342

.LBB0_1346:
	v_readlane_b32 s6, v251, 43
	v_readlane_b32 s7, v251, 44
	s_add_i32 s2, s2, 1
	s_mov_b64 s[40:41], -1
	s_nop 2
	global_load_dword v0, v97, s[6:7] sc1
	s_waitcnt vmcnt(0)
	v_cmp_ne_u32_e32 vcc, v0, v1
	s_orn2_b64 s[38:39], vcc, exec
	s_branch .LBB0_1341
